# in-proj tile prologue: 16 shift@W partial-sum loads issued together instead of 16 serialized round trips
# speedup vs baseline: 1.0416x; 1.0231x over previous
.LBB0_192:
	s_or_saveexec_b64 s[52:53], s[52:53]
	v_mov_b64_e32 v[2:3], s[88:89]
	s_xor_b64 exec, exec, s[52:53]
	s_cbranch_execz .LBB0_194
	s_add_i32 s13, s63, 0xfffff000
	s_lshr_b32 s13, s13, 11
	s_add_i32 s13, s13, 1
	s_cmpk_gt_i32 s12, 0xfff
	s_cselect_b32 s13, s13, 0
	s_mul_i32 s23, s86, 5
	s_add_i32 s13, s13, s23
	s_mul_hi_u32 s23, s13, 0x2400
	s_mulk_i32 s13, 0x2400
	s_add_u32 s13, s21, s13
	s_addc_u32 s23, s24, s23
	s_ashr_i32 s89, s88, 31
	s_lshl_b64 s[54:55], s[88:89], 2
	s_add_u32 s54, s13, s54
	s_addc_u32 s55, s23, s55
	v_ashrrev_i32_e32 v1, 31, v0
	v_lshl_add_u64 v[2:3], v[0:1], 2, s[54:55]
	s_mov_b64 s[54:55], 0x2d000
	global_load_dword v16, v[2:3], off
	v_lshl_add_u64 v[4:5], v[2:3], 0, s[54:55]
	global_load_dword v17, v[4:5], off
	v_lshl_add_u64 v[4:5], v[4:5], 0, s[54:55]
	global_load_dword v18, v[4:5], off
	v_lshl_add_u64 v[4:5], v[4:5], 0, s[54:55]
	global_load_dword v19, v[4:5], off
	v_lshl_add_u64 v[4:5], v[4:5], 0, s[54:55]
	global_load_dword v20, v[4:5], off
	v_lshl_add_u64 v[4:5], v[4:5], 0, s[54:55]
	global_load_dword v21, v[4:5], off
	v_lshl_add_u64 v[4:5], v[4:5], 0, s[54:55]
	global_load_dword v22, v[4:5], off
	v_lshl_add_u64 v[4:5], v[4:5], 0, s[54:55]
	global_load_dword v23, v[4:5], off
	v_lshl_add_u64 v[4:5], v[4:5], 0, s[54:55]
	global_load_dword v24, v[4:5], off
	v_lshl_add_u64 v[4:5], v[4:5], 0, s[54:55]
	global_load_dword v25, v[4:5], off
	v_lshl_add_u64 v[4:5], v[4:5], 0, s[54:55]
	global_load_dword v26, v[4:5], off
	v_lshl_add_u64 v[4:5], v[4:5], 0, s[54:55]
	global_load_dword v27, v[4:5], off
	v_lshl_add_u64 v[4:5], v[4:5], 0, s[54:55]
	global_load_dword v28, v[4:5], off
	v_lshl_add_u64 v[4:5], v[4:5], 0, s[54:55]
	global_load_dword v29, v[4:5], off
	v_lshl_add_u64 v[4:5], v[4:5], 0, s[54:55]
	global_load_dword v30, v[4:5], off
	v_lshl_add_u64 v[4:5], v[4:5], 0, s[54:55]
	global_load_dword v31, v[4:5], off
	s_waitcnt vmcnt(15)
	v_add_f32_e32 v1, 0, v16
	s_waitcnt vmcnt(14)
	v_add_f32_e32 v1, v1, v17
	s_waitcnt vmcnt(13)
	v_add_f32_e32 v1, v1, v18
	s_waitcnt vmcnt(12)
	v_add_f32_e32 v1, v1, v19
	s_waitcnt vmcnt(11)
	v_add_f32_e32 v1, v1, v20
	s_waitcnt vmcnt(10)
	v_add_f32_e32 v1, v1, v21
	s_waitcnt vmcnt(9)
	v_add_f32_e32 v1, v1, v22
	s_waitcnt vmcnt(8)
	v_add_f32_e32 v1, v1, v23
	s_waitcnt vmcnt(7)
	v_add_f32_e32 v1, v1, v24
	s_waitcnt vmcnt(6)
	v_add_f32_e32 v1, v1, v25
	s_waitcnt vmcnt(5)
	v_add_f32_e32 v1, v1, v26
	s_waitcnt vmcnt(4)
	v_add_f32_e32 v1, v1, v27
	s_waitcnt vmcnt(3)
	v_add_f32_e32 v1, v1, v28
	s_waitcnt vmcnt(2)
	v_add_f32_e32 v1, v1, v29
	s_waitcnt vmcnt(1)
	v_add_f32_e32 v1, v1, v30
	s_waitcnt vmcnt(0)
	v_add_f32_e32 v1, v1, v31
	v_mov_b32_e32 v2, 0x21000
	v_lshl_add_u32 v0, v0, 2, v2
	v_mov_b64_e32 v[2:3], s[88:89]
	ds_write_b32 v0, v1
